# v69 + row-max chain head trimmed (three canonicalising max ops -> one) in the three attention loops
# baseline (speedup 1.0000x reference)
; template <int DQK, int KROW, bool BIAS, bool MAPS2>
; DI void attn_core(const int t, const u16* __restrict__ Q, int ldq, const u16* __restrict__ Kp, int ldk, const u16* __restrict__ Vt, int q0,
;                   char* lds, const float* lut, float b31, f32x16 (&o)[4], float& l_out) {
;     ...
;       float mx = s[0][0];
; #pragma unroll
;       for (int k2 = 0; k2 < 2; ++k2)
; #pragma unroll
;         for (int i = 0; i < 16; ++i) mx = fmaxf(mx, s[k2][i]);
;       mx = xhalf_max(mx);
;       if (__builtin_amdgcn_ballot_w64(kt == 0 || mx > RESCALE_THR)) {
;         const float delta = (kt == 0) ? mx : fmaxf(mx, 0.f);
;         const float alpha = __builtin_amdgcn_exp2f(-delta);
;         m_run += delta;
;         l_run *= alpha;
; #pragma unroll
;         for (int dt = 0; dt < 4; ++dt)
; #pragma unroll
;           for (int i = 0; i < 16; ++i) o[dt][i] *= alpha;
; #pragma unroll
;         for (int k2 = 0; k2 < 2; ++k2)
; #pragma unroll
;           for (int i = 0; i < 16; ++i) s[k2][i] -= delta;
;       }
.LBB0_238:
	s_or_b64 exec, exec, s[0:1]
	s_nop 4
	s_nop 0
	v_max_f32_e32 v0, v96, v97
	v_max3_f32 v0, v0, v98, v99
	v_max3_f32 v0, v0, v100, v101
	v_max3_f32 v0, v0, v102, v103
	v_max3_f32 v0, v0, v104, v105
	v_max3_f32 v0, v0, v106, v107
	v_max3_f32 v0, v0, v108, v109
	v_max3_f32 v0, v0, v110, v111
	v_max3_f32 v0, v0, v80, v81
	v_max3_f32 v0, v0, v82, v83
	v_max3_f32 v0, v0, v84, v85
	v_max3_f32 v0, v0, v86, v87
	v_max3_f32 v0, v0, v88, v89
	v_max3_f32 v0, v0, v90, v91
	v_max3_f32 v0, v0, v92, v93
	v_max3_f32 v0, v0, v94, v95
	v_mov_b32_e32 v2, v0
	s_nop 1
	v_permlane32_swap_b32_e32 v0, v2
	v_max_f32_e32 v0, v0, v2
	s_cmp_eq_u32 s96, 0
	s_cselect_b64 s[0:1], -1, 0
	v_cmp_lt_f32_e32 vcc, s6, v0
	s_or_b64 vcc, s[0:1], vcc
	s_cbranch_vccz .LBB0_242
	v_max_f32_e32 v2, v0, v0
	v_max_f32_e32 v2, 0, v2
	v_cndmask_b32_e64 v0, v2, v0, s[0:1]
	v_exp_f32_e64 v2, -v0
	v_add_f32_e32 v161, v161, v0
	v_pk_add_f32 v[96:97], v[96:97], v[0:1] op_sel_hi:[1,0] neg_lo:[0,1] neg_hi:[0,1]
	v_pk_add_f32 v[98:99], v[98:99], v[0:1] op_sel_hi:[1,0] neg_lo:[0,1] neg_hi:[0,1]
	v_pk_mul_f32 v[78:79], v[78:79], v[2:3] op_sel_hi:[1,0]
	v_pk_mul_f32 v[76:77], v[76:77], v[2:3] op_sel_hi:[1,0]
	v_pk_mul_f32 v[74:75], v[74:75], v[2:3] op_sel_hi:[1,0]
	v_pk_mul_f32 v[72:73], v[72:73], v[2:3] op_sel_hi:[1,0]
	v_pk_mul_f32 v[70:71], v[70:71], v[2:3] op_sel_hi:[1,0]
	v_pk_mul_f32 v[68:69], v[68:69], v[2:3] op_sel_hi:[1,0]
	v_pk_mul_f32 v[66:67], v[66:67], v[2:3] op_sel_hi:[1,0]
	v_pk_mul_f32 v[64:65], v[64:65], v[2:3] op_sel_hi:[1,0]
	v_pk_mul_f32 v[62:63], v[62:63], v[2:3] op_sel_hi:[1,0]
	v_pk_mul_f32 v[60:61], v[60:61], v[2:3] op_sel_hi:[1,0]
	v_pk_mul_f32 v[58:59], v[58:59], v[2:3] op_sel_hi:[1,0]
	v_pk_mul_f32 v[56:57], v[56:57], v[2:3] op_sel_hi:[1,0]
	v_pk_mul_f32 v[54:55], v[54:55], v[2:3] op_sel_hi:[1,0]
	v_pk_mul_f32 v[52:53], v[52:53], v[2:3] op_sel_hi:[1,0]
	v_pk_mul_f32 v[50:51], v[50:51], v[2:3] op_sel_hi:[1,0]
	v_pk_mul_f32 v[48:49], v[48:49], v[2:3] op_sel_hi:[1,0]
	v_pk_mul_f32 v[46:47], v[46:47], v[2:3] op_sel_hi:[1,0]
	v_pk_mul_f32 v[44:45], v[44:45], v[2:3] op_sel_hi:[1,0]
	v_pk_mul_f32 v[42:43], v[42:43], v[2:3] op_sel_hi:[1,0]
	v_pk_mul_f32 v[40:41], v[40:41], v[2:3] op_sel_hi:[1,0]
	v_pk_mul_f32 v[38:39], v[38:39], v[2:3] op_sel_hi:[1,0]
	v_pk_mul_f32 v[36:37], v[36:37], v[2:3] op_sel_hi:[1,0]
	v_pk_mul_f32 v[34:35], v[34:35], v[2:3] op_sel_hi:[1,0]
	v_pk_mul_f32 v[32:33], v[32:33], v[2:3] op_sel_hi:[1,0]
	v_pk_mul_f32 v[30:31], v[30:31], v[2:3] op_sel_hi:[1,0]
	v_pk_mul_f32 v[28:29], v[28:29], v[2:3] op_sel_hi:[1,0]
	v_pk_mul_f32 v[26:27], v[26:27], v[2:3] op_sel_hi:[1,0]
	v_pk_mul_f32 v[24:25], v[24:25], v[2:3] op_sel_hi:[1,0]
	v_pk_mul_f32 v[22:23], v[22:23], v[2:3] op_sel_hi:[1,0]
	v_pk_mul_f32 v[20:21], v[20:21], v[2:3] op_sel_hi:[1,0]
	v_pk_mul_f32 v[18:19], v[18:19], v[2:3] op_sel_hi:[1,0]
	v_pk_mul_f32 v[16:17], v[16:17], v[2:3] op_sel_hi:[1,0]
	v_pk_add_f32 v[100:101], v[100:101], v[0:1] op_sel_hi:[1,0] neg_lo:[0,1] neg_hi:[0,1]
	v_pk_add_f32 v[102:103], v[102:103], v[0:1] op_sel_hi:[1,0] neg_lo:[0,1] neg_hi:[0,1]
	v_pk_add_f32 v[104:105], v[104:105], v[0:1] op_sel_hi:[1,0] neg_lo:[0,1] neg_hi:[0,1]
	v_pk_add_f32 v[106:107], v[106:107], v[0:1] op_sel_hi:[1,0] neg_lo:[0,1] neg_hi:[0,1]
	v_pk_add_f32 v[108:109], v[108:109], v[0:1] op_sel_hi:[1,0] neg_lo:[0,1] neg_hi:[0,1]
	v_pk_add_f32 v[110:111], v[110:111], v[0:1] op_sel_hi:[1,0] neg_lo:[0,1] neg_hi:[0,1]
	v_pk_add_f32 v[80:81], v[80:81], v[0:1] op_sel_hi:[1,0] neg_lo:[0,1] neg_hi:[0,1]
	v_pk_add_f32 v[82:83], v[82:83], v[0:1] op_sel_hi:[1,0] neg_lo:[0,1] neg_hi:[0,1]
	v_pk_add_f32 v[84:85], v[84:85], v[0:1] op_sel_hi:[1,0] neg_lo:[0,1] neg_hi:[0,1]
	v_pk_add_f32 v[86:87], v[86:87], v[0:1] op_sel_hi:[1,0] neg_lo:[0,1] neg_hi:[0,1]
	v_pk_add_f32 v[88:89], v[88:89], v[0:1] op_sel_hi:[1,0] neg_lo:[0,1] neg_hi:[0,1]
	v_pk_add_f32 v[90:91], v[90:91], v[0:1] op_sel_hi:[1,0] neg_lo:[0,1] neg_hi:[0,1]
	v_pk_add_f32 v[92:93], v[92:93], v[0:1] op_sel_hi:[1,0] neg_lo:[0,1] neg_hi:[0,1]
	v_pk_add_f32 v[94:95], v[94:95], v[0:1] op_sel_hi:[1,0] neg_lo:[0,1] neg_hi:[0,1]
	v_mul_f32_e32 v151, v151, v2

; template <int DQK, int KROW, bool BIAS, bool MAPS2>
; DI void attn_core(const int t, const u16* __restrict__ Q, int ldq, const u16* __restrict__ Kp, int ldk, const u16* __restrict__ Vt, int q0,
;                   char* lds, const float* lut, float b31, f32x16 (&o)[4], float& l_out) {
;     ...
;       float mx = s[0][0];
; #pragma unroll
;       for (int k2 = 0; k2 < 2; ++k2)
; #pragma unroll
;         for (int i = 0; i < 16; ++i) mx = fmaxf(mx, s[k2][i]);
;       mx = xhalf_max(mx);
;       if (__builtin_amdgcn_ballot_w64(kt == 0 || mx > RESCALE_THR)) {
;         const float delta = (kt == 0) ? mx : fmaxf(mx, 0.f);
;         const float alpha = __builtin_amdgcn_exp2f(-delta);
;         m_run += delta;
;         l_run *= alpha;
; #pragma unroll
;         for (int dt = 0; dt < 4; ++dt)
; #pragma unroll
;           for (int i = 0; i < 16; ++i) o[dt][i] *= alpha;
; #pragma unroll
;         for (int k2 = 0; k2 < 2; ++k2)
; #pragma unroll
;           for (int i = 0; i < 16; ++i) s[k2][i] -= delta;
;       }
.LBB0_259:
	s_or_b64 exec, exec, s[0:1]
	s_nop 3
	v_max_f32_e32 v181, v82, v83
	v_max3_f32 v181, v181, v84, v85
	v_max3_f32 v181, v181, v86, v87
	v_max3_f32 v181, v181, v88, v89
	v_max3_f32 v181, v181, v90, v91
	v_max3_f32 v181, v181, v92, v93
	v_max3_f32 v181, v181, v94, v95
	v_max3_f32 v181, v181, v96, v97
	v_max3_f32 v181, v181, v66, v67
	v_max3_f32 v181, v181, v68, v69
	v_max3_f32 v181, v181, v70, v71
	v_max3_f32 v181, v181, v72, v73
	v_max3_f32 v181, v181, v74, v75
	v_max3_f32 v181, v181, v76, v77
	v_max3_f32 v181, v181, v78, v79
	v_max3_f32 v181, v181, v80, v81
	v_mov_b32_e32 v182, v181
	s_nop 1
	v_permlane32_swap_b32_e32 v181, v182
	v_max_f32_e32 v181, v181, v182
	s_cmp_eq_u32 s93, 0
	s_cselect_b64 s[0:1], -1, 0
	v_cmp_lt_f32_e32 vcc, s6, v181
	s_or_b64 vcc, s[0:1], vcc
	s_cbranch_vccz .LBB0_261
	v_max_f32_e32 v182, v181, v181
	v_max_f32_e32 v182, 0, v182
	v_cndmask_b32_e64 v182, v182, v181, s[0:1]
	v_exp_f32_e64 v184, -v182
	v_add_f32_e32 v180, v180, v182
	v_pk_add_f32 v[82:83], v[82:83], v[182:183] op_sel_hi:[1,0] neg_lo:[0,1] neg_hi:[0,1]
	v_pk_add_f32 v[84:85], v[84:85], v[182:183] op_sel_hi:[1,0] neg_lo:[0,1] neg_hi:[0,1]
	v_pk_mul_f32 v[64:65], v[64:65], v[184:185] op_sel_hi:[1,0]
	v_pk_mul_f32 v[62:63], v[62:63], v[184:185] op_sel_hi:[1,0]
	v_pk_mul_f32 v[60:61], v[60:61], v[184:185] op_sel_hi:[1,0]
	v_pk_mul_f32 v[58:59], v[58:59], v[184:185] op_sel_hi:[1,0]
	v_pk_mul_f32 v[56:57], v[56:57], v[184:185] op_sel_hi:[1,0]
	v_pk_mul_f32 v[54:55], v[54:55], v[184:185] op_sel_hi:[1,0]
	v_pk_mul_f32 v[52:53], v[52:53], v[184:185] op_sel_hi:[1,0]
	v_pk_mul_f32 v[50:51], v[50:51], v[184:185] op_sel_hi:[1,0]
	v_pk_mul_f32 v[48:49], v[48:49], v[184:185] op_sel_hi:[1,0]
	v_pk_mul_f32 v[46:47], v[46:47], v[184:185] op_sel_hi:[1,0]
	v_pk_mul_f32 v[44:45], v[44:45], v[184:185] op_sel_hi:[1,0]
	v_pk_mul_f32 v[42:43], v[42:43], v[184:185] op_sel_hi:[1,0]
	v_pk_mul_f32 v[40:41], v[40:41], v[184:185] op_sel_hi:[1,0]
	v_pk_mul_f32 v[38:39], v[38:39], v[184:185] op_sel_hi:[1,0]
	v_pk_mul_f32 v[36:37], v[36:37], v[184:185] op_sel_hi:[1,0]
	v_pk_mul_f32 v[34:35], v[34:35], v[184:185] op_sel_hi:[1,0]
	v_pk_mul_f32 v[32:33], v[32:33], v[184:185] op_sel_hi:[1,0]
	v_pk_mul_f32 v[30:31], v[30:31], v[184:185] op_sel_hi:[1,0]
	v_pk_mul_f32 v[28:29], v[28:29], v[184:185] op_sel_hi:[1,0]
	v_pk_mul_f32 v[26:27], v[26:27], v[184:185] op_sel_hi:[1,0]
	v_pk_mul_f32 v[24:25], v[24:25], v[184:185] op_sel_hi:[1,0]
	v_pk_mul_f32 v[22:23], v[22:23], v[184:185] op_sel_hi:[1,0]
	v_pk_mul_f32 v[20:21], v[20:21], v[184:185] op_sel_hi:[1,0]
	v_pk_mul_f32 v[18:19], v[18:19], v[184:185] op_sel_hi:[1,0]
	v_pk_mul_f32 v[16:17], v[16:17], v[184:185] op_sel_hi:[1,0]
	v_pk_mul_f32 v[14:15], v[14:15], v[184:185] op_sel_hi:[1,0]
	v_pk_mul_f32 v[12:13], v[12:13], v[184:185] op_sel_hi:[1,0]
	v_pk_mul_f32 v[10:11], v[10:11], v[184:185] op_sel_hi:[1,0]
	v_pk_mul_f32 v[8:9], v[8:9], v[184:185] op_sel_hi:[1,0]
	v_pk_mul_f32 v[6:7], v[6:7], v[184:185] op_sel_hi:[1,0]
	v_pk_mul_f32 v[4:5], v[4:5], v[184:185] op_sel_hi:[1,0]
	v_pk_mul_f32 v[2:3], v[2:3], v[184:185] op_sel_hi:[1,0]
	v_pk_add_f32 v[86:87], v[86:87], v[182:183] op_sel_hi:[1,0] neg_lo:[0,1] neg_hi:[0,1]
	v_pk_add_f32 v[88:89], v[88:89], v[182:183] op_sel_hi:[1,0] neg_lo:[0,1] neg_hi:[0,1]
	v_pk_add_f32 v[90:91], v[90:91], v[182:183] op_sel_hi:[1,0] neg_lo:[0,1] neg_hi:[0,1]
	v_pk_add_f32 v[92:93], v[92:93], v[182:183] op_sel_hi:[1,0] neg_lo:[0,1] neg_hi:[0,1]
	v_pk_add_f32 v[94:95], v[94:95], v[182:183] op_sel_hi:[1,0] neg_lo:[0,1] neg_hi:[0,1]
	v_pk_add_f32 v[96:97], v[96:97], v[182:183] op_sel_hi:[1,0] neg_lo:[0,1] neg_hi:[0,1]
	v_pk_add_f32 v[66:67], v[66:67], v[182:183] op_sel_hi:[1,0] neg_lo:[0,1] neg_hi:[0,1]
	v_pk_add_f32 v[68:69], v[68:69], v[182:183] op_sel_hi:[1,0] neg_lo:[0,1] neg_hi:[0,1]
	v_pk_add_f32 v[70:71], v[70:71], v[182:183] op_sel_hi:[1,0] neg_lo:[0,1] neg_hi:[0,1]
	v_pk_add_f32 v[72:73], v[72:73], v[182:183] op_sel_hi:[1,0] neg_lo:[0,1] neg_hi:[0,1]
	v_pk_add_f32 v[74:75], v[74:75], v[182:183] op_sel_hi:[1,0] neg_lo:[0,1] neg_hi:[0,1]
	v_pk_add_f32 v[76:77], v[76:77], v[182:183] op_sel_hi:[1,0] neg_lo:[0,1] neg_hi:[0,1]
	v_pk_add_f32 v[78:79], v[78:79], v[182:183] op_sel_hi:[1,0] neg_lo:[0,1] neg_hi:[0,1]
	v_pk_add_f32 v[80:81], v[80:81], v[182:183] op_sel_hi:[1,0] neg_lo:[0,1] neg_hi:[0,1]
	v_mul_f32_e32 v0, v0, v184

; template <int DQK, int KROW, bool BIAS, bool MAPS2>
; DI void attn_core(const int t, const u16* __restrict__ Q, int ldq, const u16* __restrict__ Kp, int ldk, const u16* __restrict__ Vt, int q0,
;                   char* lds, const float* lut, float b31, f32x16 (&o)[4], float& l_out) {
;     ...
;       float mx = s[0][0];
; #pragma unroll
;       for (int k2 = 0; k2 < 2; ++k2)
; #pragma unroll
;         for (int i = 0; i < 16; ++i) mx = fmaxf(mx, s[k2][i]);
;       mx = xhalf_max(mx);
;       if (__builtin_amdgcn_ballot_w64(kt == 0 || mx > RESCALE_THR)) {
;         const float delta = (kt == 0) ? mx : fmaxf(mx, 0.f);
;         const float alpha = __builtin_amdgcn_exp2f(-delta);
;         m_run += delta;
;         l_run *= alpha;
; #pragma unroll
;         for (int dt = 0; dt < 4; ++dt)
; #pragma unroll
;           for (int i = 0; i < 16; ++i) o[dt][i] *= alpha;
; #pragma unroll
;         for (int k2 = 0; k2 < 2; ++k2)
; #pragma unroll
;           for (int i = 0; i < 16; ++i) s[k2][i] -= delta;
;       }
.LBB0_273:
	s_or_b64 exec, exec, s[0:1]
	s_nop 3
	v_max_f32_e32 v181, v82, v83
	v_max3_f32 v181, v181, v84, v85
	v_max3_f32 v181, v181, v86, v87
	v_max3_f32 v181, v181, v88, v89
	v_max3_f32 v181, v181, v90, v91
	v_max3_f32 v181, v181, v92, v93
	v_max3_f32 v181, v181, v94, v95
	v_max3_f32 v181, v181, v96, v97
	v_max3_f32 v181, v181, v66, v67
	v_max3_f32 v181, v181, v68, v69
	v_max3_f32 v181, v181, v70, v71
	v_max3_f32 v181, v181, v72, v73
	v_max3_f32 v181, v181, v74, v75
	v_max3_f32 v181, v181, v76, v77
	v_max3_f32 v181, v181, v78, v79
	v_max3_f32 v181, v181, v80, v81
	v_mov_b32_e32 v182, v181
	s_nop 1
	v_permlane32_swap_b32_e32 v181, v182
	v_max_f32_e32 v181, v181, v182
	s_cmp_eq_u32 s63, 0
	s_cselect_b64 s[0:1], -1, 0
	v_cmp_lt_f32_e32 vcc, s6, v181
	s_or_b64 vcc, s[0:1], vcc
	s_cbranch_vccz .LBB0_275
	v_max_f32_e32 v182, v181, v181
	v_max_f32_e32 v182, 0, v182
	v_cndmask_b32_e64 v182, v182, v181, s[0:1]
	v_exp_f32_e64 v184, -v182
	v_add_f32_e32 v180, v180, v182
	v_pk_add_f32 v[82:83], v[82:83], v[182:183] op_sel_hi:[1,0] neg_lo:[0,1] neg_hi:[0,1]
	v_pk_add_f32 v[84:85], v[84:85], v[182:183] op_sel_hi:[1,0] neg_lo:[0,1] neg_hi:[0,1]
	v_pk_mul_f32 v[64:65], v[64:65], v[184:185] op_sel_hi:[1,0]
	v_pk_mul_f32 v[62:63], v[62:63], v[184:185] op_sel_hi:[1,0]
	v_pk_mul_f32 v[60:61], v[60:61], v[184:185] op_sel_hi:[1,0]
	v_pk_mul_f32 v[58:59], v[58:59], v[184:185] op_sel_hi:[1,0]
	v_pk_mul_f32 v[56:57], v[56:57], v[184:185] op_sel_hi:[1,0]
	v_pk_mul_f32 v[54:55], v[54:55], v[184:185] op_sel_hi:[1,0]
	v_pk_mul_f32 v[52:53], v[52:53], v[184:185] op_sel_hi:[1,0]
	v_pk_mul_f32 v[50:51], v[50:51], v[184:185] op_sel_hi:[1,0]
	v_pk_mul_f32 v[48:49], v[48:49], v[184:185] op_sel_hi:[1,0]
	v_pk_mul_f32 v[46:47], v[46:47], v[184:185] op_sel_hi:[1,0]
	v_pk_mul_f32 v[44:45], v[44:45], v[184:185] op_sel_hi:[1,0]
	v_pk_mul_f32 v[42:43], v[42:43], v[184:185] op_sel_hi:[1,0]
	v_pk_mul_f32 v[40:41], v[40:41], v[184:185] op_sel_hi:[1,0]
	v_pk_mul_f32 v[38:39], v[38:39], v[184:185] op_sel_hi:[1,0]
	v_pk_mul_f32 v[36:37], v[36:37], v[184:185] op_sel_hi:[1,0]
	v_pk_mul_f32 v[34:35], v[34:35], v[184:185] op_sel_hi:[1,0]
	v_pk_mul_f32 v[32:33], v[32:33], v[184:185] op_sel_hi:[1,0]
	v_pk_mul_f32 v[30:31], v[30:31], v[184:185] op_sel_hi:[1,0]
	v_pk_mul_f32 v[28:29], v[28:29], v[184:185] op_sel_hi:[1,0]
	v_pk_mul_f32 v[26:27], v[26:27], v[184:185] op_sel_hi:[1,0]
	v_pk_mul_f32 v[24:25], v[24:25], v[184:185] op_sel_hi:[1,0]
	v_pk_mul_f32 v[22:23], v[22:23], v[184:185] op_sel_hi:[1,0]
	v_pk_mul_f32 v[20:21], v[20:21], v[184:185] op_sel_hi:[1,0]
	v_pk_mul_f32 v[18:19], v[18:19], v[184:185] op_sel_hi:[1,0]
	v_pk_mul_f32 v[16:17], v[16:17], v[184:185] op_sel_hi:[1,0]
	v_pk_mul_f32 v[14:15], v[14:15], v[184:185] op_sel_hi:[1,0]
	v_pk_mul_f32 v[12:13], v[12:13], v[184:185] op_sel_hi:[1,0]
	v_pk_mul_f32 v[10:11], v[10:11], v[184:185] op_sel_hi:[1,0]
	v_pk_mul_f32 v[8:9], v[8:9], v[184:185] op_sel_hi:[1,0]
	v_pk_mul_f32 v[6:7], v[6:7], v[184:185] op_sel_hi:[1,0]
	v_pk_mul_f32 v[4:5], v[4:5], v[184:185] op_sel_hi:[1,0]
	v_pk_mul_f32 v[2:3], v[2:3], v[184:185] op_sel_hi:[1,0]
	v_pk_add_f32 v[86:87], v[86:87], v[182:183] op_sel_hi:[1,0] neg_lo:[0,1] neg_hi:[0,1]
	v_pk_add_f32 v[88:89], v[88:89], v[182:183] op_sel_hi:[1,0] neg_lo:[0,1] neg_hi:[0,1]
	v_pk_add_f32 v[90:91], v[90:91], v[182:183] op_sel_hi:[1,0] neg_lo:[0,1] neg_hi:[0,1]
	v_pk_add_f32 v[92:93], v[92:93], v[182:183] op_sel_hi:[1,0] neg_lo:[0,1] neg_hi:[0,1]
	v_pk_add_f32 v[94:95], v[94:95], v[182:183] op_sel_hi:[1,0] neg_lo:[0,1] neg_hi:[0,1]
	v_pk_add_f32 v[96:97], v[96:97], v[182:183] op_sel_hi:[1,0] neg_lo:[0,1] neg_hi:[0,1]
	v_pk_add_f32 v[66:67], v[66:67], v[182:183] op_sel_hi:[1,0] neg_lo:[0,1] neg_hi:[0,1]
	v_pk_add_f32 v[68:69], v[68:69], v[182:183] op_sel_hi:[1,0] neg_lo:[0,1] neg_hi:[0,1]
	v_pk_add_f32 v[70:71], v[70:71], v[182:183] op_sel_hi:[1,0] neg_lo:[0,1] neg_hi:[0,1]
	v_pk_add_f32 v[72:73], v[72:73], v[182:183] op_sel_hi:[1,0] neg_lo:[0,1] neg_hi:[0,1]
	v_pk_add_f32 v[74:75], v[74:75], v[182:183] op_sel_hi:[1,0] neg_lo:[0,1] neg_hi:[0,1]
	v_pk_add_f32 v[76:77], v[76:77], v[182:183] op_sel_hi:[1,0] neg_lo:[0,1] neg_hi:[0,1]
	v_pk_add_f32 v[78:79], v[78:79], v[182:183] op_sel_hi:[1,0] neg_lo:[0,1] neg_hi:[0,1]
	v_pk_add_f32 v[80:81], v[80:81], v[182:183] op_sel_hi:[1,0] neg_lo:[0,1] neg_hi:[0,1]
	v_mul_f32_e32 v0, v0, v184
